# weight conversion: batches of 8 adjacent tiles along the source rows (2 KB contiguous reads), all in flight
# baseline (speedup 1.0000x reference)
; __device__ __forceinline__ int fresh_bid() { int t; asm volatile("s_mov_b32 %0, %1" : "=s"(t) : "s"(blockIdx.x)); return t; }
; __device__ __forceinline__ void phase_convert(const Ctx& a, int l, LAS unsigned char* lds) {
;     ...
;     for (int j = 0; j < 10; ++j) {
;         CJob c = get_job(j, a, l);
;         const int nkt = c.K / 64, nnt = c.Ntot / 64, ntile = nkt * nnt;
;         int first = (int)((fresh_bid() + gridDim.x - (base % gridDim.x)) % gridDim.x);
;         float pv[8];
;     ...
;         if (first < ntile) CV_LOAD(first);
;         for (int i = first; i < ntile; i += gridDim.x) {
.LBB0_717:
	s_mov_b32 s30, s2
	s_load_dword s9, s[74:75], 0x0
	s_lshr_b32 s46, s51, 3
	s_lshr_b32 s52, s26, 0
	s_mul_i32 s52, s52, s46
	v_cvt_f32_u32_e32 v22, s51
	s_waitcnt lgkmcnt(0)
	v_cvt_f32_u32_e32 v21, s9
	s_sub_i32 s26, 0, s9
	v_rcp_iflag_f32_e32 v21, v21
	s_nop 0
	v_mul_f32_e32 v21, 0x4f7ffffe, v21
	v_cvt_u32_f32_e32 v23, v21
	v_rcp_iflag_f32_e32 v21, v22
	v_readfirstlane_b32 s42, v23
	s_mul_i32 s26, s26, s42
	s_mul_hi_u32 s26, s42, s26
	s_add_i32 s42, s42, s26
	s_mul_hi_u32 s26, s48, s42
	s_mul_i32 s26, s26, s9
	s_sub_i32 s26, s48, s26
	s_sub_i32 s43, s26, s9
	s_cmp_ge_u32 s26, s9
	s_cselect_b32 s26, s43, s26
	s_sub_i32 s43, s26, s9
	s_cmp_ge_u32 s26, s9
	s_cselect_b32 s26, s43, s26
	s_add_i32 s30, s9, s30
	s_sub_i32 s26, s30, s26
	s_mul_hi_u32 s30, s26, s42
	s_mul_i32 s30, s30, s9
	s_sub_i32 s26, s26, s30
	s_sub_i32 s30, s26, s9
	s_cmp_ge_u32 s26, s9
	s_cselect_b32 s26, s30, s26
	s_sub_i32 s30, s26, s9
	s_cmp_ge_u32 s26, s9
	s_cselect_b32 s53, s30, s26
	s_cmp_lt_i32 s53, s52
	s_cselect_b64 s[44:45], -1, 0
	s_cmp_ge_i32 s53, s52
	s_cbranch_scc1 .LBB0_693
	s_waitcnt vmcnt(0) lgkmcnt(0)
	v_cvt_f32_u32_e32 v21, s46
	v_rcp_iflag_f32_e32 v21, v21
	s_nop 0
	v_mul_f32_e32 v21, 0x4f7ffffe, v21
	v_cvt_u32_f32_e32 v21, v21
	s_sub_i32 s26, 0, s46
	v_readfirstlane_b32 s44, v21
	v_readfirstlane_b32 s56, v14
	v_readfirstlane_b32 s57, v15
	v_readfirstlane_b32 s58, v16
	v_readfirstlane_b32 s59, v17
	s_xor_b64 s[42:43], s[36:37], -1
	v_cmp_ne_u64_e64 s[36:37], 0, v[16:17]
	s_nop 3
	s_mul_i32 s26, s26, s44
	s_mul_hi_u32 s26, s44, s26
	s_add_i32 s54, s44, s26
	s_lshl_b64 s[44:45], s[40:41], 1
	s_add_u32 s38, s38, s44
	s_addc_u32 s39, s39, s45
	s_lshl_b64 s[40:41], s[0:1], 5
	v_lshlrev_b32_e32 v175, 2, v2
	v_add_u32_e32 v32, 0x10400, v20
	v_mov_b32_e32 v42, 1.0
	v_mov_b32_e32 v43, 1.0
	v_mov_b32_e32 v44, 1.0
	v_mov_b32_e32 v45, 1.0
	v_mov_b32_e32 v46, 1.0
	v_mov_b32_e32 v47, 1.0
	v_mov_b32_e32 v48, 1.0
	v_mov_b32_e32 v49, 1.0
	s_mov_b32 s60, 0
	s_cmp_ge_i32 s53, s52
	s_cbranch_scc1 .Lcv_isd_a
	s_mul_hi_u32 s26, s53, s54
	s_mul_i32 s55, s26, s46
	s_sub_i32 s55, s53, s55
	s_sub_i32 s61, s55, s46
	s_add_i32 s62, s26, 1
	s_cmp_ge_u32 s55, s46
	s_cselect_b32 s26, s62, s26
	s_cselect_b32 s55, s61, s55
	s_sub_i32 s61, s55, s46
	s_add_i32 s62, s26, 1
	s_cmp_ge_u32 s55, s46
	s_cselect_b32 s26, s62, s26
	s_cselect_b32 s55, s61, s55
	s_lshl_b32 s47, s26, 6
	s_lshl_b32 s63, s55, 9
	s_add_i32 s30, s50, -1
	s_add_i32 s62, s63, 0
	s_add_i32 s61, s47, 0
	v_add_u32_e32 v162, s62, v1
	v_min_u32_e32 v170, s30, v162
	v_add_u32_e32 v171, s61, v2
	v_mad_u32_u24 v170, v171, s0, v170
	v_lshlrev_b32_e32 v170, 2, v170
	s_mov_b64 s[44:45], s[56:57]
	global_load_dword v34, v170, s[44:45] nt
	s_add_u32 s44, s44, s40
	s_addc_u32 s45, s45, s41
	global_load_dword v35, v170, s[44:45] nt
	s_add_u32 s44, s44, s40
	s_addc_u32 s45, s45, s41
	global_load_dword v36, v170, s[44:45] nt
	s_add_u32 s44, s44, s40
	s_addc_u32 s45, s45, s41
	global_load_dword v37, v170, s[44:45] nt
	s_add_u32 s44, s44, s40
	s_addc_u32 s45, s45, s41
	global_load_dword v38, v170, s[44:45] nt
	s_add_u32 s44, s44, s40
	s_addc_u32 s45, s45, s41
	global_load_dword v39, v170, s[44:45] nt
	s_add_u32 s44, s44, s40
	s_addc_u32 s45, s45, s41
	global_load_dword v40, v170, s[44:45] nt
	s_add_u32 s44, s44, s40
	s_addc_u32 s45, s45, s41
	global_load_dword v41, v170, s[44:45] nt
	s_cmp_eq_u64 s[36:37], 0
	s_cbranch_scc1 .Lcv_ng_a_0
	s_lshl_b32 s61, s61, 2
	s_add_u32 s44, s58, s61
	s_addc_u32 s45, s59, 0
	global_load_dword v42, v175, s[44:45] offset:0
	global_load_dword v43, v175, s[44:45] offset:32
	global_load_dword v44, v175, s[44:45] offset:64
	global_load_dword v45, v175, s[44:45] offset:96
	global_load_dword v46, v175, s[44:45] offset:128
	global_load_dword v47, v175, s[44:45] offset:160
	global_load_dword v48, v175, s[44:45] offset:192
	global_load_dword v49, v175, s[44:45] offset:224
; __device__ __forceinline__ int fresh_bid() { int t; asm volatile("s_mov_b32 %0, %1" : "=s"(t) : "s"(blockIdx.x)); return t; }
; __device__ __forceinline__ void phase_convert(const Ctx& a, int l, LAS unsigned char* lds) {
;     ...
;         int first = (int)((fresh_bid() + gridDim.x - (base % gridDim.x)) % gridDim.x);
;         float pv[8];
.Lcv_ng_a_0:
	s_add_i32 s62, s63, 64
	s_add_i32 s61, s47, 0
	v_add_u32_e32 v163, s62, v1
	v_min_u32_e32 v170, s30, v163
	v_add_u32_e32 v171, s61, v2
	v_mad_u32_u24 v170, v171, s0, v170
	v_lshlrev_b32_e32 v170, 2, v170
	s_mov_b64 s[44:45], s[56:57]
	global_load_dword v50, v170, s[44:45] nt
	s_add_u32 s44, s44, s40
	s_addc_u32 s45, s45, s41
	global_load_dword v51, v170, s[44:45] nt
	s_add_u32 s44, s44, s40
	s_addc_u32 s45, s45, s41
	global_load_dword v52, v170, s[44:45] nt
	s_add_u32 s44, s44, s40
	s_addc_u32 s45, s45, s41
	global_load_dword v53, v170, s[44:45] nt
	s_add_u32 s44, s44, s40
	s_addc_u32 s45, s45, s41
	global_load_dword v54, v170, s[44:45] nt
	s_add_u32 s44, s44, s40
	s_addc_u32 s45, s45, s41
	global_load_dword v55, v170, s[44:45] nt
	s_add_u32 s44, s44, s40
	s_addc_u32 s45, s45, s41
	global_load_dword v56, v170, s[44:45] nt
	s_add_u32 s44, s44, s40
	s_addc_u32 s45, s45, s41
	global_load_dword v57, v170, s[44:45] nt
	s_add_i32 s62, s63, 128
	s_add_i32 s61, s47, 0
	v_add_u32_e32 v164, s62, v1
	v_min_u32_e32 v170, s30, v164
	v_add_u32_e32 v171, s61, v2
	v_mad_u32_u24 v170, v171, s0, v170
	v_lshlrev_b32_e32 v170, 2, v170
	s_mov_b64 s[44:45], s[56:57]
	global_load_dword v66, v170, s[44:45] nt
	s_add_u32 s44, s44, s40
	s_addc_u32 s45, s45, s41
	global_load_dword v67, v170, s[44:45] nt
	s_add_u32 s44, s44, s40
	s_addc_u32 s45, s45, s41
	global_load_dword v68, v170, s[44:45] nt
	s_add_u32 s44, s44, s40
	s_addc_u32 s45, s45, s41
	global_load_dword v69, v170, s[44:45] nt
	s_add_u32 s44, s44, s40
	s_addc_u32 s45, s45, s41
	global_load_dword v70, v170, s[44:45] nt
	s_add_u32 s44, s44, s40
	s_addc_u32 s45, s45, s41
	global_load_dword v71, v170, s[44:45] nt
	s_add_u32 s44, s44, s40
	s_addc_u32 s45, s45, s41
	global_load_dword v72, v170, s[44:45] nt
	s_add_u32 s44, s44, s40
	s_addc_u32 s45, s45, s41
	global_load_dword v73, v170, s[44:45] nt
	s_add_i32 s62, s63, 192
	s_add_i32 s61, s47, 0
	v_add_u32_e32 v165, s62, v1
	v_min_u32_e32 v170, s30, v165
	v_add_u32_e32 v171, s61, v2
	v_mad_u32_u24 v170, v171, s0, v170
	v_lshlrev_b32_e32 v170, 2, v170
	s_mov_b64 s[44:45], s[56:57]
	global_load_dword v82, v170, s[44:45] nt
	s_add_u32 s44, s44, s40
	s_addc_u32 s45, s45, s41
	global_load_dword v83, v170, s[44:45] nt
	s_add_u32 s44, s44, s40
	s_addc_u32 s45, s45, s41
	global_load_dword v84, v170, s[44:45] nt
	s_add_u32 s44, s44, s40
	s_addc_u32 s45, s45, s41
	global_load_dword v85, v170, s[44:45] nt
	s_add_u32 s44, s44, s40
	s_addc_u32 s45, s45, s41
	global_load_dword v86, v170, s[44:45] nt
	s_add_u32 s44, s44, s40
	s_addc_u32 s45, s45, s41
	global_load_dword v87, v170, s[44:45] nt
	s_add_u32 s44, s44, s40
	s_addc_u32 s45, s45, s41
	global_load_dword v88, v170, s[44:45] nt
	s_add_u32 s44, s44, s40
	s_addc_u32 s45, s45, s41
	global_load_dword v89, v170, s[44:45] nt
	s_add_i32 s62, s63, 256
	s_add_i32 s61, s47, 0
	v_add_u32_e32 v166, s62, v1
	v_min_u32_e32 v170, s30, v166
	v_add_u32_e32 v171, s61, v2
	v_mad_u32_u24 v170, v171, s0, v170
	v_lshlrev_b32_e32 v170, 2, v170
	s_mov_b64 s[44:45], s[56:57]
	global_load_dword v98, v170, s[44:45] nt
	s_add_u32 s44, s44, s40
	s_addc_u32 s45, s45, s41
	global_load_dword v99, v170, s[44:45] nt
	s_add_u32 s44, s44, s40
	s_addc_u32 s45, s45, s41
	global_load_dword v100, v170, s[44:45] nt
	s_add_u32 s44, s44, s40
	s_addc_u32 s45, s45, s41
	global_load_dword v101, v170, s[44:45] nt
	s_add_u32 s44, s44, s40
	s_addc_u32 s45, s45, s41
	global_load_dword v102, v170, s[44:45] nt
	s_add_u32 s44, s44, s40
	s_addc_u32 s45, s45, s41
	global_load_dword v103, v170, s[44:45] nt
	s_add_u32 s44, s44, s40
	s_addc_u32 s45, s45, s41
	global_load_dword v104, v170, s[44:45] nt
	s_add_u32 s44, s44, s40
	s_addc_u32 s45, s45, s41
	global_load_dword v105, v170, s[44:45] nt
	s_add_i32 s62, s63, 320
	s_add_i32 s61, s47, 0
	v_add_u32_e32 v167, s62, v1
	v_min_u32_e32 v170, s30, v167
	v_add_u32_e32 v171, s61, v2
	v_mad_u32_u24 v170, v171, s0, v170
	v_lshlrev_b32_e32 v170, 2, v170
	s_mov_b64 s[44:45], s[56:57]
	global_load_dword v114, v170, s[44:45] nt
	s_add_u32 s44, s44, s40
	s_addc_u32 s45, s45, s41
	global_load_dword v115, v170, s[44:45] nt
	s_add_u32 s44, s44, s40
	s_addc_u32 s45, s45, s41
	global_load_dword v116, v170, s[44:45] nt
	s_add_u32 s44, s44, s40
	s_addc_u32 s45, s45, s41
	global_load_dword v117, v170, s[44:45] nt
	s_add_u32 s44, s44, s40
	s_addc_u32 s45, s45, s41
	global_load_dword v118, v170, s[44:45] nt
	s_add_u32 s44, s44, s40
	s_addc_u32 s45, s45, s41
	global_load_dword v119, v170, s[44:45] nt
	s_add_u32 s44, s44, s40
	s_addc_u32 s45, s45, s41
	global_load_dword v120, v170, s[44:45] nt
	s_add_u32 s44, s44, s40
	s_addc_u32 s45, s45, s41
	global_load_dword v121, v170, s[44:45] nt
	s_add_i32 s62, s63, 384
	s_add_i32 s61, s47, 0
	v_add_u32_e32 v168, s62, v1
	v_min_u32_e32 v170, s30, v168
	v_add_u32_e32 v171, s61, v2
	v_mad_u32_u24 v170, v171, s0, v170
	v_lshlrev_b32_e32 v170, 2, v170
	s_mov_b64 s[44:45], s[56:57]
	global_load_dword v130, v170, s[44:45] nt
	s_add_u32 s44, s44, s40
	s_addc_u32 s45, s45, s41
	global_load_dword v131, v170, s[44:45] nt
	s_add_u32 s44, s44, s40
	s_addc_u32 s45, s45, s41
	global_load_dword v132, v170, s[44:45] nt
	s_add_u32 s44, s44, s40
	s_addc_u32 s45, s45, s41
	global_load_dword v133, v170, s[44:45] nt
	s_add_u32 s44, s44, s40
	s_addc_u32 s45, s45, s41
	global_load_dword v134, v170, s[44:45] nt
	s_add_u32 s44, s44, s40
	s_addc_u32 s45, s45, s41
	global_load_dword v135, v170, s[44:45] nt
	s_add_u32 s44, s44, s40
	s_addc_u32 s45, s45, s41
	global_load_dword v136, v170, s[44:45] nt
	s_add_u32 s44, s44, s40
	s_addc_u32 s45, s45, s41
	global_load_dword v137, v170, s[44:45] nt
	s_add_i32 s62, s63, 448
	s_add_i32 s61, s47, 0
	v_add_u32_e32 v169, s62, v1
	v_min_u32_e32 v170, s30, v169
	v_add_u32_e32 v171, s61, v2
	v_mad_u32_u24 v170, v171, s0, v170
	v_lshlrev_b32_e32 v170, 2, v170
	s_mov_b64 s[44:45], s[56:57]
	global_load_dword v146, v170, s[44:45] nt
	s_add_u32 s44, s44, s40
	s_addc_u32 s45, s45, s41
	global_load_dword v147, v170, s[44:45] nt
	s_add_u32 s44, s44, s40
	s_addc_u32 s45, s45, s41
	global_load_dword v148, v170, s[44:45] nt
	s_add_u32 s44, s44, s40
	s_addc_u32 s45, s45, s41
	global_load_dword v149, v170, s[44:45] nt
	s_add_u32 s44, s44, s40
	s_addc_u32 s45, s45, s41
	global_load_dword v150, v170, s[44:45] nt
	s_add_u32 s44, s44, s40
	s_addc_u32 s45, s45, s41
	global_load_dword v151, v170, s[44:45] nt
	s_add_u32 s44, s44, s40
	s_addc_u32 s45, s45, s41
	global_load_dword v152, v170, s[44:45] nt
	s_add_u32 s44, s44, s40
	s_addc_u32 s45, s45, s41
	global_load_dword v153, v170, s[44:45] nt
	s_mov_b32 s60, 8

; __device__ __forceinline__ void phase_convert(const Ctx& a, int l, LAS unsigned char* lds) {
;     ...
;         if (first < ntile) CV_LOAD(first);
;         for (int i = first; i < ntile; i += gridDim.x) {
;             const int kt = i / nnt, ntl = i % nnt, k0 = kt * 64, n0 = ntl * 64;
; #pragma unroll
;             for (int it = 0; it < 8; ++it) tile[((tid >> 6) + it * 8) * 65 + (tid & 63)] = pv[it];
;             __syncthreads();
;             if (i + (int)gridDim.x < ntile) CV_LOAD(i + gridDim.x);
.Lcv_top:
	v_pk_mul_f32 v[34:35], v[34:35], v[42:43]
	v_pk_mul_f32 v[36:37], v[36:37], v[44:45]
	v_pk_mul_f32 v[38:39], v[38:39], v[46:47]
	v_pk_mul_f32 v[40:41], v[40:41], v[48:49]
	v_cmp_gt_u32_e32 vcc, s50, v162
	v_cndmask_b32_e32 v34, 0, v34, vcc
	v_cndmask_b32_e32 v35, 0, v35, vcc
	v_cndmask_b32_e32 v36, 0, v36, vcc
	v_cndmask_b32_e32 v37, 0, v37, vcc
	v_cndmask_b32_e32 v38, 0, v38, vcc
	v_cndmask_b32_e32 v39, 0, v39, vcc
	v_cndmask_b32_e32 v40, 0, v40, vcc
	v_cndmask_b32_e32 v41, 0, v41, vcc
	ds_write_b32 v20, v34 offset:0
	ds_write_b32 v20, v35 offset:2080
	ds_write_b32 v20, v36 offset:4160
	ds_write_b32 v20, v37 offset:6240
	ds_write_b32 v20, v38 offset:8320
	ds_write_b32 v20, v39 offset:10400
	ds_write_b32 v20, v40 offset:12480
	ds_write_b32 v20, v41 offset:14560
	v_pk_mul_f32 v[50:51], v[50:51], v[42:43]
	v_pk_mul_f32 v[52:53], v[52:53], v[44:45]
	v_pk_mul_f32 v[54:55], v[54:55], v[46:47]
	v_pk_mul_f32 v[56:57], v[56:57], v[48:49]
	v_cmp_gt_u32_e32 vcc, s50, v163
	v_cndmask_b32_e32 v50, 0, v50, vcc
	v_cndmask_b32_e32 v51, 0, v51, vcc
	v_cndmask_b32_e32 v52, 0, v52, vcc
	v_cndmask_b32_e32 v53, 0, v53, vcc
	v_cndmask_b32_e32 v54, 0, v54, vcc
	v_cndmask_b32_e32 v55, 0, v55, vcc
	v_cndmask_b32_e32 v56, 0, v56, vcc
	v_cndmask_b32_e32 v57, 0, v57, vcc
	ds_write_b32 v20, v50 offset:16640
	ds_write_b32 v20, v51 offset:18720
	ds_write_b32 v20, v52 offset:20800
	ds_write_b32 v20, v53 offset:22880
	ds_write_b32 v20, v54 offset:24960
	ds_write_b32 v20, v55 offset:27040
	ds_write_b32 v20, v56 offset:29120
	ds_write_b32 v20, v57 offset:31200
	v_pk_mul_f32 v[66:67], v[66:67], v[42:43]
	v_pk_mul_f32 v[68:69], v[68:69], v[44:45]
	v_pk_mul_f32 v[70:71], v[70:71], v[46:47]
	v_pk_mul_f32 v[72:73], v[72:73], v[48:49]
	v_cmp_gt_u32_e32 vcc, s50, v164
	v_cndmask_b32_e32 v66, 0, v66, vcc
	v_cndmask_b32_e32 v67, 0, v67, vcc
	v_cndmask_b32_e32 v68, 0, v68, vcc
	v_cndmask_b32_e32 v69, 0, v69, vcc
	v_cndmask_b32_e32 v70, 0, v70, vcc
	v_cndmask_b32_e32 v71, 0, v71, vcc
	v_cndmask_b32_e32 v72, 0, v72, vcc
	v_cndmask_b32_e32 v73, 0, v73, vcc
	ds_write_b32 v20, v66 offset:33280
	ds_write_b32 v20, v67 offset:35360
	ds_write_b32 v20, v68 offset:37440
	ds_write_b32 v20, v69 offset:39520
	ds_write_b32 v20, v70 offset:41600
	ds_write_b32 v20, v71 offset:43680
	ds_write_b32 v20, v72 offset:45760
	ds_write_b32 v20, v73 offset:47840
	v_pk_mul_f32 v[82:83], v[82:83], v[42:43]
	v_pk_mul_f32 v[84:85], v[84:85], v[44:45]
	v_pk_mul_f32 v[86:87], v[86:87], v[46:47]
	v_pk_mul_f32 v[88:89], v[88:89], v[48:49]
	v_cmp_gt_u32_e32 vcc, s50, v165
	v_cndmask_b32_e32 v82, 0, v82, vcc
	v_cndmask_b32_e32 v83, 0, v83, vcc
	v_cndmask_b32_e32 v84, 0, v84, vcc
	v_cndmask_b32_e32 v85, 0, v85, vcc
	v_cndmask_b32_e32 v86, 0, v86, vcc
	v_cndmask_b32_e32 v87, 0, v87, vcc
	v_cndmask_b32_e32 v88, 0, v88, vcc
	v_cndmask_b32_e32 v89, 0, v89, vcc
	ds_write_b32 v20, v82 offset:49920
	ds_write_b32 v20, v83 offset:52000
	ds_write_b32 v20, v84 offset:54080
	ds_write_b32 v20, v85 offset:56160
	ds_write_b32 v20, v86 offset:58240
	ds_write_b32 v20, v87 offset:60320
	ds_write_b32 v20, v88 offset:62400
	ds_write_b32 v20, v89 offset:64480
	v_pk_mul_f32 v[98:99], v[98:99], v[42:43]
	v_pk_mul_f32 v[100:101], v[100:101], v[44:45]
	v_pk_mul_f32 v[102:103], v[102:103], v[46:47]
	v_pk_mul_f32 v[104:105], v[104:105], v[48:49]
	v_cmp_gt_u32_e32 vcc, s50, v166
	v_cndmask_b32_e32 v98, 0, v98, vcc
	v_cndmask_b32_e32 v99, 0, v99, vcc
	v_cndmask_b32_e32 v100, 0, v100, vcc
	v_cndmask_b32_e32 v101, 0, v101, vcc
	v_cndmask_b32_e32 v102, 0, v102, vcc
	v_cndmask_b32_e32 v103, 0, v103, vcc
	v_cndmask_b32_e32 v104, 0, v104, vcc
	v_cndmask_b32_e32 v105, 0, v105, vcc
	ds_write_b32 v32, v98 offset:0
	ds_write_b32 v32, v99 offset:2080
	ds_write_b32 v32, v100 offset:4160
	ds_write_b32 v32, v101 offset:6240
	ds_write_b32 v32, v102 offset:8320
	ds_write_b32 v32, v103 offset:10400
	ds_write_b32 v32, v104 offset:12480
	ds_write_b32 v32, v105 offset:14560
	v_pk_mul_f32 v[114:115], v[114:115], v[42:43]
	v_pk_mul_f32 v[116:117], v[116:117], v[44:45]
	v_pk_mul_f32 v[118:119], v[118:119], v[46:47]
	v_pk_mul_f32 v[120:121], v[120:121], v[48:49]
	v_cmp_gt_u32_e32 vcc, s50, v167
	v_cndmask_b32_e32 v114, 0, v114, vcc
	v_cndmask_b32_e32 v115, 0, v115, vcc
	v_cndmask_b32_e32 v116, 0, v116, vcc
	v_cndmask_b32_e32 v117, 0, v117, vcc
	v_cndmask_b32_e32 v118, 0, v118, vcc
	v_cndmask_b32_e32 v119, 0, v119, vcc
	v_cndmask_b32_e32 v120, 0, v120, vcc
	v_cndmask_b32_e32 v121, 0, v121, vcc
	ds_write_b32 v32, v114 offset:16640
	ds_write_b32 v32, v115 offset:18720
	ds_write_b32 v32, v116 offset:20800
	ds_write_b32 v32, v117 offset:22880
	ds_write_b32 v32, v118 offset:24960
	ds_write_b32 v32, v119 offset:27040
	ds_write_b32 v32, v120 offset:29120
	ds_write_b32 v32, v121 offset:31200
	v_pk_mul_f32 v[130:131], v[130:131], v[42:43]
	v_pk_mul_f32 v[132:133], v[132:133], v[44:45]
	v_pk_mul_f32 v[134:135], v[134:135], v[46:47]
	v_pk_mul_f32 v[136:137], v[136:137], v[48:49]
	v_cmp_gt_u32_e32 vcc, s50, v168
	v_cndmask_b32_e32 v130, 0, v130, vcc
	v_cndmask_b32_e32 v131, 0, v131, vcc
	v_cndmask_b32_e32 v132, 0, v132, vcc
	v_cndmask_b32_e32 v133, 0, v133, vcc
	v_cndmask_b32_e32 v134, 0, v134, vcc
	v_cndmask_b32_e32 v135, 0, v135, vcc
	v_cndmask_b32_e32 v136, 0, v136, vcc
	v_cndmask_b32_e32 v137, 0, v137, vcc
	ds_write_b32 v32, v130 offset:33280
	ds_write_b32 v32, v131 offset:35360
	ds_write_b32 v32, v132 offset:37440
	ds_write_b32 v32, v133 offset:39520
	ds_write_b32 v32, v134 offset:41600
	ds_write_b32 v32, v135 offset:43680
	ds_write_b32 v32, v136 offset:45760
	ds_write_b32 v32, v137 offset:47840
	v_pk_mul_f32 v[146:147], v[146:147], v[42:43]
	v_pk_mul_f32 v[148:149], v[148:149], v[44:45]
	v_pk_mul_f32 v[150:151], v[150:151], v[46:47]
	v_pk_mul_f32 v[152:153], v[152:153], v[48:49]
	v_cmp_gt_u32_e32 vcc, s50, v169
	v_cndmask_b32_e32 v146, 0, v146, vcc
	v_cndmask_b32_e32 v147, 0, v147, vcc
	v_cndmask_b32_e32 v148, 0, v148, vcc
	v_cndmask_b32_e32 v149, 0, v149, vcc
	v_cndmask_b32_e32 v150, 0, v150, vcc
	v_cndmask_b32_e32 v151, 0, v151, vcc
	v_cndmask_b32_e32 v152, 0, v152, vcc
	v_cndmask_b32_e32 v153, 0, v153, vcc
	ds_write_b32 v32, v146 offset:49920
	ds_write_b32 v32, v147 offset:52000
	ds_write_b32 v32, v148 offset:54080
	ds_write_b32 v32, v149 offset:56160
	ds_write_b32 v32, v150 offset:58240
	ds_write_b32 v32, v151 offset:60320
	ds_write_b32 v32, v152 offset:62400
	ds_write_b32 v32, v153 offset:64480
	s_waitcnt lgkmcnt(0)
	s_barrier
; __device__ __forceinline__ void phase_convert(const Ctx& a, int l, LAS unsigned char* lds) {
;     ...
;         if (first < ntile) CV_LOAD(first);
;         for (int i = first; i < ntile; i += gridDim.x) {
;             const int kt = i / nnt, ntl = i % nnt, k0 = kt * 64, n0 = ntl * 64;
; #pragma unroll
;             for (int it = 0; it < 8; ++it) tile[((tid >> 6) + it * 8) * 65 + (tid & 63)] = pv[it];
;             __syncthreads();
;             if (i + (int)gridDim.x < ntile) CV_LOAD(i + gridDim.x);
	s_add_i32 s53, s53, s9
	s_mov_b32 s60, 0
	s_cmp_ge_i32 s53, s52
	s_cbranch_scc1 .Lcv_isd_b
	s_mul_hi_u32 s26, s53, s54
	s_mul_i32 s55, s26, s46
	s_sub_i32 s55, s53, s55
	s_sub_i32 s61, s55, s46
	s_add_i32 s62, s26, 1
	s_cmp_ge_u32 s55, s46
	s_cselect_b32 s26, s62, s26
	s_cselect_b32 s55, s61, s55
	s_sub_i32 s61, s55, s46
	s_add_i32 s62, s26, 1
	s_cmp_ge_u32 s55, s46
	s_cselect_b32 s26, s62, s26
	s_cselect_b32 s55, s61, s55
	s_lshl_b32 s47, s26, 6
	s_lshl_b32 s63, s55, 9
	s_add_i32 s30, s50, -1
	s_add_i32 s62, s63, 0
	s_add_i32 s61, s47, 0
	v_add_u32_e32 v162, s62, v1
	v_min_u32_e32 v170, s30, v162
	v_add_u32_e32 v171, s61, v2
	v_mad_u32_u24 v170, v171, s0, v170
	v_lshlrev_b32_e32 v170, 2, v170
	s_mov_b64 s[44:45], s[56:57]
	global_load_dword v34, v170, s[44:45] nt
	s_add_u32 s44, s44, s40
	s_addc_u32 s45, s45, s41
	global_load_dword v35, v170, s[44:45] nt
	s_add_u32 s44, s44, s40
	s_addc_u32 s45, s45, s41
	global_load_dword v36, v170, s[44:45] nt
	s_add_u32 s44, s44, s40
	s_addc_u32 s45, s45, s41
	global_load_dword v37, v170, s[44:45] nt
	s_add_u32 s44, s44, s40
	s_addc_u32 s45, s45, s41
	global_load_dword v38, v170, s[44:45] nt
	s_add_u32 s44, s44, s40
	s_addc_u32 s45, s45, s41
	global_load_dword v39, v170, s[44:45] nt
	s_add_u32 s44, s44, s40
	s_addc_u32 s45, s45, s41
	global_load_dword v40, v170, s[44:45] nt
	s_add_u32 s44, s44, s40
	s_addc_u32 s45, s45, s41
	global_load_dword v41, v170, s[44:45] nt
	s_cmp_eq_u64 s[36:37], 0
	s_cbranch_scc1 .Lcv_ng_b_0
	s_lshl_b32 s61, s61, 2
	s_add_u32 s44, s58, s61
	s_addc_u32 s45, s59, 0
	global_load_dword v42, v175, s[44:45] offset:0
	global_load_dword v43, v175, s[44:45] offset:32
	global_load_dword v44, v175, s[44:45] offset:64
	global_load_dword v45, v175, s[44:45] offset:96
	global_load_dword v46, v175, s[44:45] offset:128
	global_load_dword v47, v175, s[44:45] offset:160
	global_load_dword v48, v175, s[44:45] offset:192
	global_load_dword v49, v175, s[44:45] offset:224

; __device__ __forceinline__ unsigned cvt_pk(float lo, float hi) { f32x2_t v = {lo, hi}; bf16x2_t b = __builtin_convertvector(v, bf16x2_t); return __builtin_bit_cast(unsigned, b); }
; __device__ __forceinline__ void phase_convert(const Ctx& a, int l, LAS unsigned char* lds) {
;     ...
;             {
;                 int nn = tid >> 3, kc = (tid & 7) * 8, n = n0 + nn, row = n;
;                 if (c.perm) { if (n < FF) row = (n / 128) * 256 + (n % 128); else { int jn = n - FF; row = (jn / 128) * 256 + 128 + (jn % 128); } }
;                 u32x4 w;
;                 w[0] = cvt_pk(tile[(kc + 0) * 65 + nn], tile[(kc + 1) * 65 + nn]);
;                 w[1] = cvt_pk(tile[(kc + 2) * 65 + nn], tile[(kc + 3) * 65 + nn]);
;                 w[2] = cvt_pk(tile[(kc + 4) * 65 + nn], tile[(kc + 5) * 65 + nn]);
;                 w[3] = cvt_pk(tile[(kc + 6) * 65 + nn], tile[(kc + 7) * 65 + nn]);
;                 *(u32x4*)(c.dst + (size_t)row * c.lddst + c.koff + k0 + kc) = w;
;             }
.Lcv_isd_b:
	s_sub_i32 s30, s53, s9
	s_mul_hi_u32 s26, s30, s54
	s_mul_i32 s55, s26, s46
	s_sub_i32 s55, s30, s55
	s_sub_i32 s61, s55, s46
	s_add_i32 s62, s26, 1
	s_cmp_ge_u32 s55, s46
	s_cselect_b32 s26, s62, s26
	s_cselect_b32 s55, s61, s55
	s_sub_i32 s61, s55, s46
	s_add_i32 s62, s26, 1
	s_cmp_ge_u32 s55, s46
	s_cselect_b32 s26, s62, s26
	s_cselect_b32 s55, s61, s55
	s_lshl_b32 s47, s26, 7
	s_lshl_b32 s63, s55, 9
	s_add_i32 s62, s63, 0
	s_add_i32 s61, s47, 0
	v_add_u32_e32 v172, s62, v11
	v_cmp_gt_u32_e32 vcc, 0xb00, v172
	v_subrev_u32_e32 v173, 0xb00, v172
	v_cndmask_b32_e32 v173, v173, v172, vcc
	v_lshrrev_b32_e32 v174, 7, v173
	v_and_b32_e32 v173, 0x7f, v173
	v_lshl_or_b32 v173, v174, 8, v173
	v_mov_b32_e32 v174, 0x80
	v_cndmask_b32_e32 v174, v174, v145, vcc
	v_or_b32_e32 v173, v173, v174
	v_cndmask_b32_e64 v172, v172, v173, s[42:43]
	v_mul_u32_u24_e32 v173, s12, v172
	v_lshl_add_u32 v173, v173, 1, v144
	s_add_u32 s44, s38, s61
	s_addc_u32 s45, s39, 0
	v_add_u32_e32 v176, 0x0, v18
	v_add_u32_e32 v177, 0x400, v18
	ds_read2_b32 v[24:25], v176 offset1:65
	ds_read2_b32 v[26:27], v176 offset0:130 offset1:195
	ds_read2_b32 v[28:29], v177 offset0:4 offset1:69
	ds_read2_b32 v[30:31], v177 offset0:134 offset1:199
	s_waitcnt lgkmcnt(0)
	v_cvt_pk_bf16_f32 v4, v24, v25
	v_cvt_pk_bf16_f32 v5, v26, v27
	v_cvt_pk_bf16_f32 v6, v28, v29
	v_cvt_pk_bf16_f32 v7, v30, v31
	global_store_dwordx4 v173, v[4:7], s[44:45]
	s_add_i32 s62, s63, 64
	s_add_i32 s61, s47, 0
	v_add_u32_e32 v172, s62, v11
	v_cmp_gt_u32_e32 vcc, 0xb00, v172
	v_subrev_u32_e32 v173, 0xb00, v172
	v_cndmask_b32_e32 v173, v173, v172, vcc
	v_lshrrev_b32_e32 v174, 7, v173
	v_and_b32_e32 v173, 0x7f, v173
	v_lshl_or_b32 v173, v174, 8, v173
	v_mov_b32_e32 v174, 0x80
	v_cndmask_b32_e32 v174, v174, v145, vcc
	v_or_b32_e32 v173, v173, v174
	v_cndmask_b32_e64 v172, v172, v173, s[42:43]
	v_mul_u32_u24_e32 v173, s12, v172
	v_lshl_add_u32 v173, v173, 1, v144
	s_add_u32 s44, s38, s61
	s_addc_u32 s45, s39, 0
	v_add_u32_e32 v176, 0x4100, v18
	v_add_u32_e32 v177, 0x4500, v18
	ds_read2_b32 v[24:25], v176 offset1:65
	ds_read2_b32 v[26:27], v176 offset0:130 offset1:195
	ds_read2_b32 v[28:29], v177 offset0:4 offset1:69
	ds_read2_b32 v[30:31], v177 offset0:134 offset1:199
	s_waitcnt lgkmcnt(0)
	v_cvt_pk_bf16_f32 v12, v24, v25
	v_cvt_pk_bf16_f32 v13, v26, v27
	v_cvt_pk_bf16_f32 v14, v28, v29
	v_cvt_pk_bf16_f32 v15, v30, v31
	global_store_dwordx4 v173, v[12:15], s[44:45]
	s_add_i32 s62, s63, 128
	s_add_i32 s61, s47, 0
	v_add_u32_e32 v172, s62, v11
	v_cmp_gt_u32_e32 vcc, 0xb00, v172
	v_subrev_u32_e32 v173, 0xb00, v172
	v_cndmask_b32_e32 v173, v173, v172, vcc
	v_lshrrev_b32_e32 v174, 7, v173
	v_and_b32_e32 v173, 0x7f, v173
	v_lshl_or_b32 v173, v174, 8, v173
	v_mov_b32_e32 v174, 0x80
	v_cndmask_b32_e32 v174, v174, v145, vcc
	v_or_b32_e32 v173, v173, v174
	v_cndmask_b32_e64 v172, v172, v173, s[42:43]
	v_mul_u32_u24_e32 v173, s12, v172
	v_lshl_add_u32 v173, v173, 1, v144
	s_add_u32 s44, s38, s61
	s_addc_u32 s45, s39, 0
	v_add_u32_e32 v176, 0x8200, v18
	v_add_u32_e32 v177, 0x8600, v18
	ds_read2_b32 v[24:25], v176 offset1:65
	ds_read2_b32 v[26:27], v176 offset0:130 offset1:195
	ds_read2_b32 v[28:29], v177 offset0:4 offset1:69
	ds_read2_b32 v[30:31], v177 offset0:134 offset1:199
	s_waitcnt lgkmcnt(0)
	v_cvt_pk_bf16_f32 v4, v24, v25
	v_cvt_pk_bf16_f32 v5, v26, v27
	v_cvt_pk_bf16_f32 v6, v28, v29
	v_cvt_pk_bf16_f32 v7, v30, v31
	global_store_dwordx4 v173, v[4:7], s[44:45]
	s_add_i32 s62, s63, 192
	s_add_i32 s61, s47, 0
	v_add_u32_e32 v172, s62, v11
	v_cmp_gt_u32_e32 vcc, 0xb00, v172
	v_subrev_u32_e32 v173, 0xb00, v172
	v_cndmask_b32_e32 v173, v173, v172, vcc
	v_lshrrev_b32_e32 v174, 7, v173
	v_and_b32_e32 v173, 0x7f, v173
	v_lshl_or_b32 v173, v174, 8, v173
	v_mov_b32_e32 v174, 0x80
	v_cndmask_b32_e32 v174, v174, v145, vcc
	v_or_b32_e32 v173, v173, v174
	v_cndmask_b32_e64 v172, v172, v173, s[42:43]
	v_mul_u32_u24_e32 v173, s12, v172
	v_lshl_add_u32 v173, v173, 1, v144
	s_add_u32 s44, s38, s61
	s_addc_u32 s45, s39, 0
	v_add_u32_e32 v176, 0xc300, v18
	v_add_u32_e32 v177, 0xc700, v18
	ds_read2_b32 v[24:25], v176 offset1:65
	ds_read2_b32 v[26:27], v176 offset0:130 offset1:195
	ds_read2_b32 v[28:29], v177 offset0:4 offset1:69
	ds_read2_b32 v[30:31], v177 offset0:134 offset1:199
	s_waitcnt lgkmcnt(0)
; __device__ __forceinline__ unsigned cvt_pk(float lo, float hi) { f32x2_t v = {lo, hi}; bf16x2_t b = __builtin_convertvector(v, bf16x2_t); return __builtin_bit_cast(unsigned, b); }
; __device__ __forceinline__ void phase_convert(const Ctx& a, int l, LAS unsigned char* lds) {
;     ...
;             {
;                 int nn = tid >> 3, kc = (tid & 7) * 8, n = n0 + nn, row = n;
;                 if (c.perm) { if (n < FF) row = (n / 128) * 256 + (n % 128); else { int jn = n - FF; row = (jn / 128) * 256 + 128 + (jn % 128); } }
;                 u32x4 w;
;                 w[0] = cvt_pk(tile[(kc + 0) * 65 + nn], tile[(kc + 1) * 65 + nn]);
;                 w[1] = cvt_pk(tile[(kc + 2) * 65 + nn], tile[(kc + 3) * 65 + nn]);
;                 w[2] = cvt_pk(tile[(kc + 4) * 65 + nn], tile[(kc + 5) * 65 + nn]);
;                 w[3] = cvt_pk(tile[(kc + 6) * 65 + nn], tile[(kc + 7) * 65 + nn]);
;                 *(u32x4*)(c.dst + (size_t)row * c.lddst + c.koff + k0 + kc) = w;
;             }
;             __syncthreads();
	v_cvt_pk_bf16_f32 v12, v24, v25
	v_cvt_pk_bf16_f32 v13, v26, v27
	v_cvt_pk_bf16_f32 v14, v28, v29
	v_cvt_pk_bf16_f32 v15, v30, v31
	global_store_dwordx4 v173, v[12:15], s[44:45]
	s_add_i32 s62, s63, 256
	s_add_i32 s61, s47, 0
	v_add_u32_e32 v172, s62, v11
	v_cmp_gt_u32_e32 vcc, 0xb00, v172
	v_subrev_u32_e32 v173, 0xb00, v172
	v_cndmask_b32_e32 v173, v173, v172, vcc
	v_lshrrev_b32_e32 v174, 7, v173
	v_and_b32_e32 v173, 0x7f, v173
	v_lshl_or_b32 v173, v174, 8, v173
	v_mov_b32_e32 v174, 0x80
	v_cndmask_b32_e32 v174, v174, v145, vcc
	v_or_b32_e32 v173, v173, v174
	v_cndmask_b32_e64 v172, v172, v173, s[42:43]
	v_mul_u32_u24_e32 v173, s12, v172
	v_lshl_add_u32 v173, v173, 1, v144
	s_add_u32 s44, s38, s61
	s_addc_u32 s45, s39, 0
	v_add_u32_e32 v176, 0x10400, v18
	v_add_u32_e32 v177, 0x10800, v18
	ds_read2_b32 v[24:25], v176 offset1:65
	ds_read2_b32 v[26:27], v176 offset0:130 offset1:195
	ds_read2_b32 v[28:29], v177 offset0:4 offset1:69
	ds_read2_b32 v[30:31], v177 offset0:134 offset1:199
	s_waitcnt lgkmcnt(0)
	v_cvt_pk_bf16_f32 v4, v24, v25
	v_cvt_pk_bf16_f32 v5, v26, v27
	v_cvt_pk_bf16_f32 v6, v28, v29
	v_cvt_pk_bf16_f32 v7, v30, v31
	global_store_dwordx4 v173, v[4:7], s[44:45]
	s_add_i32 s62, s63, 320
	s_add_i32 s61, s47, 0
	v_add_u32_e32 v172, s62, v11
	v_cmp_gt_u32_e32 vcc, 0xb00, v172
	v_subrev_u32_e32 v173, 0xb00, v172
	v_cndmask_b32_e32 v173, v173, v172, vcc
	v_lshrrev_b32_e32 v174, 7, v173
	v_and_b32_e32 v173, 0x7f, v173
	v_lshl_or_b32 v173, v174, 8, v173
	v_mov_b32_e32 v174, 0x80
	v_cndmask_b32_e32 v174, v174, v145, vcc
	v_or_b32_e32 v173, v173, v174
	v_cndmask_b32_e64 v172, v172, v173, s[42:43]
	v_mul_u32_u24_e32 v173, s12, v172
	v_lshl_add_u32 v173, v173, 1, v144
	s_add_u32 s44, s38, s61
	s_addc_u32 s45, s39, 0
	v_add_u32_e32 v176, 0x14500, v18
	v_add_u32_e32 v177, 0x14900, v18
	ds_read2_b32 v[24:25], v176 offset1:65
	ds_read2_b32 v[26:27], v176 offset0:130 offset1:195
	ds_read2_b32 v[28:29], v177 offset0:4 offset1:69
	ds_read2_b32 v[30:31], v177 offset0:134 offset1:199
	s_waitcnt lgkmcnt(0)
	v_cvt_pk_bf16_f32 v12, v24, v25
	v_cvt_pk_bf16_f32 v13, v26, v27
	v_cvt_pk_bf16_f32 v14, v28, v29
	v_cvt_pk_bf16_f32 v15, v30, v31
	global_store_dwordx4 v173, v[12:15], s[44:45]
	s_add_i32 s62, s63, 384
	s_add_i32 s61, s47, 0
	v_add_u32_e32 v172, s62, v11
	v_cmp_gt_u32_e32 vcc, 0xb00, v172
	v_subrev_u32_e32 v173, 0xb00, v172
	v_cndmask_b32_e32 v173, v173, v172, vcc
	v_lshrrev_b32_e32 v174, 7, v173
	v_and_b32_e32 v173, 0x7f, v173
	v_lshl_or_b32 v173, v174, 8, v173
	v_mov_b32_e32 v174, 0x80
	v_cndmask_b32_e32 v174, v174, v145, vcc
	v_or_b32_e32 v173, v173, v174
	v_cndmask_b32_e64 v172, v172, v173, s[42:43]
	v_mul_u32_u24_e32 v173, s12, v172
	v_lshl_add_u32 v173, v173, 1, v144
	s_add_u32 s44, s38, s61
	s_addc_u32 s45, s39, 0
	v_add_u32_e32 v176, 0x18600, v18
	v_add_u32_e32 v177, 0x18a00, v18
	ds_read2_b32 v[24:25], v176 offset1:65
	ds_read2_b32 v[26:27], v176 offset0:130 offset1:195
	ds_read2_b32 v[28:29], v177 offset0:4 offset1:69
	ds_read2_b32 v[30:31], v177 offset0:134 offset1:199
	s_waitcnt lgkmcnt(0)
	v_cvt_pk_bf16_f32 v4, v24, v25
	v_cvt_pk_bf16_f32 v5, v26, v27
	v_cvt_pk_bf16_f32 v6, v28, v29
	v_cvt_pk_bf16_f32 v7, v30, v31
	global_store_dwordx4 v173, v[4:7], s[44:45]
	s_add_i32 s62, s63, 448
	s_add_i32 s61, s47, 0
	v_add_u32_e32 v172, s62, v11
	v_cmp_gt_u32_e32 vcc, 0xb00, v172
	v_subrev_u32_e32 v173, 0xb00, v172
	v_cndmask_b32_e32 v173, v173, v172, vcc
	v_lshrrev_b32_e32 v174, 7, v173
	v_and_b32_e32 v173, 0x7f, v173
	v_lshl_or_b32 v173, v174, 8, v173
	v_mov_b32_e32 v174, 0x80
	v_cndmask_b32_e32 v174, v174, v145, vcc
	v_or_b32_e32 v173, v173, v174
	v_cndmask_b32_e64 v172, v172, v173, s[42:43]
	v_mul_u32_u24_e32 v173, s12, v172
	v_lshl_add_u32 v173, v173, 1, v144
	s_add_u32 s44, s38, s61
	s_addc_u32 s45, s39, 0
	v_add_u32_e32 v176, 0x1c700, v18
	v_add_u32_e32 v177, 0x1cb00, v18
	ds_read2_b32 v[24:25], v176 offset1:65
	ds_read2_b32 v[26:27], v176 offset0:130 offset1:195
	ds_read2_b32 v[28:29], v177 offset0:4 offset1:69
	ds_read2_b32 v[30:31], v177 offset0:134 offset1:199
	s_waitcnt lgkmcnt(0)
	v_cvt_pk_bf16_f32 v12, v24, v25
	v_cvt_pk_bf16_f32 v13, v26, v27
	v_cvt_pk_bf16_f32 v14, v28, v29
	v_cvt_pk_bf16_f32 v15, v30, v31
	global_store_dwordx4 v173, v[12:15], s[44:45]
	s_barrier
	s_cmp_eq_u32 s60, 0
	s_cbranch_scc1 .LBB0_693
	s_waitcnt vmcnt(0)
	s_branch .Lcv_top
